# S5 chunk body: no lgkmcnt(0) drain between the wave's own LDS writes and reads (in-order LDS; counted waits only) (v60 + s5 nowait)
# speedup vs baseline: 1.0018x; 1.0018x over previous
.LBB0_844:
	s_or_b64 exec, exec, s[12:13]
	v_mfma_f32_16x16x32_bf16 v[132:135], v[4:7], v[68:71], 0
	v_mfma_f32_16x16x32_bf16 v[136:139], v[8:11], v[68:71], 0
	v_mfma_f32_16x16x32_bf16 v[140:143], v[12:15], v[68:71], 0
	v_mfma_f32_16x16x32_bf16 v[144:147], v[16:19], v[68:71], 0
	v_mfma_f32_16x16x32_bf16 v[148:151], v[20:23], v[68:71], 0
	v_mfma_f32_16x16x32_bf16 v[152:155], v[24:27], v[68:71], 0
	v_mfma_f32_16x16x32_bf16 v[156:159], v[28:31], v[68:71], 0
	v_mfma_f32_16x16x32_bf16 v[160:163], v[32:35], v[68:71], 0
	v_add_u32_e32 v196, v89, v93
	ds_write_b128 v196, v[132:135]
	ds_write_b128 v196, v[136:139] offset:64
	ds_write_b128 v196, v[140:143] offset:128
	ds_write_b128 v196, v[144:147] offset:192
	ds_write_b128 v196, v[148:151] offset:256
	ds_write_b128 v196, v[152:155] offset:320
	ds_write_b128 v196, v[156:159] offset:384
	ds_write_b128 v196, v[160:163] offset:448
	s_and_b64 s[14:15], s[0:1], exec
	s_cbranch_scc0 .Ls5c_bwd
	ds_read_b64 v[164:165], v95
	ds_read_b64 v[166:167], v95 offset:528
	ds_read_b64 v[168:169], v95 offset:1056
	ds_read_b64 v[170:171], v95 offset:1584
	ds_read_b64 v[172:173], v95 offset:2112
	ds_read_b64 v[174:175], v95 offset:2640
	ds_read_b64 v[176:177], v95 offset:3168
	ds_read_b64 v[178:179], v95 offset:3696
	s_waitcnt lgkmcnt(7)
	v_fma_f32 v164, -v72, v121, v164
	v_fma_f32 v165, v72, v120, v165
	v_fma_f32 v164, v74, v120, v164
	v_fma_f32 v165, v74, v121, v165
	v_cvt_pk_bf16_f32 v197, v164, v165
	ds_write_b32 v97, v197 offset:8448
	ds_read_b64 v[180:181], v95 offset:4224
	s_waitcnt lgkmcnt(8)
	v_fma_f32 v166, -v72, v165, v166
	v_fma_f32 v167, v72, v164, v167
	v_fma_f32 v166, v74, v164, v166
	v_fma_f32 v167, v74, v165, v167
	v_cvt_pk_bf16_f32 v198, v166, v167
	ds_write_b32 v97, v198 offset:8720
	ds_read_b64 v[182:183], v95 offset:4752
	s_waitcnt lgkmcnt(9)
	v_fma_f32 v168, -v72, v167, v168
	v_fma_f32 v169, v72, v166, v169
	v_fma_f32 v168, v74, v166, v168
	v_fma_f32 v169, v74, v167, v169
	v_cvt_pk_bf16_f32 v197, v168, v169
	ds_write_b32 v97, v197 offset:8992
	ds_read_b64 v[184:185], v95 offset:5280
	s_waitcnt lgkmcnt(10)
	v_fma_f32 v170, -v72, v169, v170
	v_fma_f32 v171, v72, v168, v171
	v_fma_f32 v170, v74, v168, v170
	v_fma_f32 v171, v74, v169, v171
	v_cvt_pk_bf16_f32 v198, v170, v171
	ds_write_b32 v97, v198 offset:9264
	ds_read_b64 v[186:187], v95 offset:5808
	s_waitcnt lgkmcnt(11)
	v_fma_f32 v172, -v72, v171, v172
	v_fma_f32 v173, v72, v170, v173
	v_fma_f32 v172, v74, v170, v172
	v_fma_f32 v173, v74, v171, v173
	v_cvt_pk_bf16_f32 v197, v172, v173
	ds_write_b32 v97, v197 offset:9536
	ds_read_b64 v[188:189], v95 offset:6336
	s_waitcnt lgkmcnt(12)
	v_fma_f32 v174, -v72, v173, v174
	v_fma_f32 v175, v72, v172, v175
	v_fma_f32 v174, v74, v172, v174
	v_fma_f32 v175, v74, v173, v175
	v_cvt_pk_bf16_f32 v198, v174, v175
	ds_write_b32 v97, v198 offset:9808
	ds_read_b64 v[190:191], v95 offset:6864
	s_waitcnt lgkmcnt(13)
	v_fma_f32 v176, -v72, v175, v176
	v_fma_f32 v177, v72, v174, v177
	v_fma_f32 v176, v74, v174, v176
	v_fma_f32 v177, v74, v175, v177
	v_cvt_pk_bf16_f32 v197, v176, v177
	ds_write_b32 v97, v197 offset:10080
	ds_read_b64 v[192:193], v95 offset:7392
	s_waitcnt lgkmcnt(14)
	v_fma_f32 v178, -v72, v177, v178
	v_fma_f32 v179, v72, v176, v179
	v_fma_f32 v178, v74, v176, v178
	v_fma_f32 v179, v74, v177, v179
	v_cvt_pk_bf16_f32 v198, v178, v179
	ds_write_b32 v97, v198 offset:10352
	ds_read_b64 v[194:195], v95 offset:7920
	s_waitcnt lgkmcnt(14)
	v_fma_f32 v180, -v72, v179, v180
	v_fma_f32 v181, v72, v178, v181
	v_fma_f32 v180, v74, v178, v180
	v_fma_f32 v181, v74, v179, v181
	v_cvt_pk_bf16_f32 v197, v180, v181
	ds_write_b32 v97, v197 offset:10624
	s_waitcnt lgkmcnt(13)
	v_fma_f32 v182, -v72, v181, v182
	v_fma_f32 v183, v72, v180, v183
	v_fma_f32 v182, v74, v180, v182
	v_fma_f32 v183, v74, v181, v183
	v_cvt_pk_bf16_f32 v198, v182, v183
	ds_write_b32 v97, v198 offset:10896
	s_waitcnt lgkmcnt(12)
	v_fma_f32 v184, -v72, v183, v184
	v_fma_f32 v185, v72, v182, v185
	v_fma_f32 v184, v74, v182, v184
	v_fma_f32 v185, v74, v183, v185
	v_cvt_pk_bf16_f32 v197, v184, v185
	ds_write_b32 v97, v197 offset:11168
	s_waitcnt lgkmcnt(11)
	v_fma_f32 v186, -v72, v185, v186
	v_fma_f32 v187, v72, v184, v187
	v_fma_f32 v186, v74, v184, v186
	v_fma_f32 v187, v74, v185, v187
	v_cvt_pk_bf16_f32 v198, v186, v187
	ds_write_b32 v97, v198 offset:11440
	s_waitcnt lgkmcnt(10)
	v_fma_f32 v188, -v72, v187, v188
	v_fma_f32 v189, v72, v186, v189
	v_fma_f32 v188, v74, v186, v188
	v_fma_f32 v189, v74, v187, v189
	v_cvt_pk_bf16_f32 v197, v188, v189
	ds_write_b32 v97, v197 offset:11712
	s_waitcnt lgkmcnt(9)
	v_fma_f32 v190, -v72, v189, v190
	v_fma_f32 v191, v72, v188, v191
	v_fma_f32 v190, v74, v188, v190
	v_fma_f32 v191, v74, v189, v191
	v_cvt_pk_bf16_f32 v198, v190, v191
	ds_write_b32 v97, v198 offset:11984
	s_waitcnt lgkmcnt(8)
	v_fma_f32 v192, -v72, v191, v192
	v_fma_f32 v193, v72, v190, v193
	v_fma_f32 v192, v74, v190, v192
	v_fma_f32 v193, v74, v191, v193
	v_cvt_pk_bf16_f32 v197, v192, v193
	ds_write_b32 v97, v197 offset:12256
	s_waitcnt lgkmcnt(7)
	v_fma_f32 v194, -v72, v193, v194
	v_fma_f32 v195, v72, v192, v195
	v_fma_f32 v194, v74, v192, v194
	v_fma_f32 v195, v74, v193, v195
	v_cvt_pk_bf16_f32 v198, v194, v195
	ds_write_b32 v97, v198 offset:12528
	s_branch .Ls5c_join

.Ls5c_join:
	v_mov_b32_e32 v120, v194
	v_mov_b32_e32 v121, v195
	v_add_u32_e32 v196, v99, v93
	ds_read_b128 v[132:135], v196 offset:8448
	ds_read_b128 v[136:139], v196 offset:8512
	ds_read_b128 v[140:143], v196 offset:8576
	ds_read_b128 v[144:147], v196 offset:8640
	s_not_b32 s14, s3
	s_add_i32 s18, s2, s14
	s_and_b64 s[14:15], s[0:1], exec
	s_cselect_b32 s14, s3, s18
	s_add_i32 s3, s3, 1
	s_waitcnt lgkmcnt(3)
	v_mfma_f32_16x16x32_bf16 v[68:71], v[48:51], v[132:135], 0
	s_waitcnt lgkmcnt(2)
	v_mfma_f32_16x16x32_bf16 v[68:71], v[52:55], v[136:139], v[68:71]
	s_waitcnt lgkmcnt(1)
	v_mfma_f32_16x16x32_bf16 v[68:71], v[56:59], v[140:143], v[68:71]
	s_waitcnt lgkmcnt(0)
	v_mfma_f32_16x16x32_bf16 v[68:71], v[60:63], v[144:147], v[68:71]
	v_lshl_add_u32 v200, s14, 4, v103
	v_ashrrev_i32_e32 v201, 31, v200
	v_lshlrev_b64 v[200:201], 12, v[200:201]
	v_lshl_add_u64 v[200:201], v[78:79], 0, v[200:201]
	s_nop 3
	v_cvt_pk_bf16_f32 v68, v68, v69
	v_cvt_pk_bf16_f32 v69, v70, v71
	global_store_dwordx2 v[200:201], v[68:69], off
	s_cmp_eq_u32 s3, s2
	s_cbranch_scc1 .LBB0_848
	v_mov_b32_e32 v68, v36
	v_mov_b32_e32 v69, v37
	v_mov_b32_e32 v70, v38
	v_mov_b32_e32 v71, v39
	v_mov_b32_e32 v36, v40
	v_mov_b32_e32 v37, v41
	v_mov_b32_e32 v38, v42
	v_mov_b32_e32 v39, v43
	v_mov_b32_e32 v40, v44
	v_mov_b32_e32 v41, v45
	v_mov_b32_e32 v42, v46
	v_mov_b32_e32 v43, v47
	s_waitcnt vmcnt(1)
	v_mov_b32_e32 v44, v64
	v_mov_b32_e32 v45, v65
	v_mov_b32_e32 v46, v66
	v_mov_b32_e32 v47, v67
	s_branch .LBB0_841

.LBB0_912:
	s_or_b64 exec, exec, s[12:13]
	v_mfma_f32_16x16x32_bf16 v[132:135], v[4:7], v[68:71], 0
	v_mfma_f32_16x16x32_bf16 v[136:139], v[8:11], v[68:71], 0
	v_mfma_f32_16x16x32_bf16 v[140:143], v[12:15], v[68:71], 0
	v_mfma_f32_16x16x32_bf16 v[144:147], v[16:19], v[68:71], 0
	v_mfma_f32_16x16x32_bf16 v[148:151], v[20:23], v[68:71], 0
	v_mfma_f32_16x16x32_bf16 v[152:155], v[24:27], v[68:71], 0
	v_mfma_f32_16x16x32_bf16 v[156:159], v[28:31], v[68:71], 0
	v_mfma_f32_16x16x32_bf16 v[160:163], v[32:35], v[68:71], 0
	v_add_u32_e32 v196, v89, v93
	ds_write_b128 v196, v[132:135]
	ds_write_b128 v196, v[136:139] offset:64
	ds_write_b128 v196, v[140:143] offset:128
	ds_write_b128 v196, v[144:147] offset:192
	ds_write_b128 v196, v[148:151] offset:256
	ds_write_b128 v196, v[152:155] offset:320
	ds_write_b128 v196, v[156:159] offset:384
	ds_write_b128 v196, v[160:163] offset:448
	s_and_b64 s[12:13], s[54:55], exec
	s_cbranch_scc0 .Ls5l_bwd
	ds_read_b64 v[164:165], v95
	ds_read_b64 v[166:167], v95 offset:528
	ds_read_b64 v[168:169], v95 offset:1056
	ds_read_b64 v[170:171], v95 offset:1584
	ds_read_b64 v[172:173], v95 offset:2112
	ds_read_b64 v[174:175], v95 offset:2640
	ds_read_b64 v[176:177], v95 offset:3168
	ds_read_b64 v[178:179], v95 offset:3696
	s_waitcnt lgkmcnt(7)
	v_fma_f32 v164, -v72, v121, v164
	v_fma_f32 v165, v72, v120, v165
	v_fma_f32 v164, v74, v120, v164
	v_fma_f32 v165, v74, v121, v165
	v_cvt_pk_bf16_f32 v197, v164, v165
	ds_write_b32 v97, v197 offset:8448
	ds_read_b64 v[180:181], v95 offset:4224
	s_waitcnt lgkmcnt(8)
	v_fma_f32 v166, -v72, v165, v166
	v_fma_f32 v167, v72, v164, v167
	v_fma_f32 v166, v74, v164, v166
	v_fma_f32 v167, v74, v165, v167
	v_cvt_pk_bf16_f32 v198, v166, v167
	ds_write_b32 v97, v198 offset:8720
	ds_read_b64 v[182:183], v95 offset:4752
	s_waitcnt lgkmcnt(9)
	v_fma_f32 v168, -v72, v167, v168
	v_fma_f32 v169, v72, v166, v169
	v_fma_f32 v168, v74, v166, v168
	v_fma_f32 v169, v74, v167, v169
	v_cvt_pk_bf16_f32 v197, v168, v169
	ds_write_b32 v97, v197 offset:8992
	ds_read_b64 v[184:185], v95 offset:5280
	s_waitcnt lgkmcnt(10)
	v_fma_f32 v170, -v72, v169, v170
	v_fma_f32 v171, v72, v168, v171
	v_fma_f32 v170, v74, v168, v170
	v_fma_f32 v171, v74, v169, v171
	v_cvt_pk_bf16_f32 v198, v170, v171
	ds_write_b32 v97, v198 offset:9264
	ds_read_b64 v[186:187], v95 offset:5808
	s_waitcnt lgkmcnt(11)
	v_fma_f32 v172, -v72, v171, v172
	v_fma_f32 v173, v72, v170, v173
	v_fma_f32 v172, v74, v170, v172
	v_fma_f32 v173, v74, v171, v173
	v_cvt_pk_bf16_f32 v197, v172, v173
	ds_write_b32 v97, v197 offset:9536
	ds_read_b64 v[188:189], v95 offset:6336
	s_waitcnt lgkmcnt(12)
	v_fma_f32 v174, -v72, v173, v174
	v_fma_f32 v175, v72, v172, v175
	v_fma_f32 v174, v74, v172, v174
	v_fma_f32 v175, v74, v173, v175
	v_cvt_pk_bf16_f32 v198, v174, v175
	ds_write_b32 v97, v198 offset:9808
	ds_read_b64 v[190:191], v95 offset:6864
	s_waitcnt lgkmcnt(13)
	v_fma_f32 v176, -v72, v175, v176
	v_fma_f32 v177, v72, v174, v177
	v_fma_f32 v176, v74, v174, v176
	v_fma_f32 v177, v74, v175, v177
	v_cvt_pk_bf16_f32 v197, v176, v177
	ds_write_b32 v97, v197 offset:10080
	ds_read_b64 v[192:193], v95 offset:7392
	s_waitcnt lgkmcnt(14)
	v_fma_f32 v178, -v72, v177, v178
	v_fma_f32 v179, v72, v176, v179
	v_fma_f32 v178, v74, v176, v178
	v_fma_f32 v179, v74, v177, v179
	v_cvt_pk_bf16_f32 v198, v178, v179
	ds_write_b32 v97, v198 offset:10352
	ds_read_b64 v[194:195], v95 offset:7920
	s_waitcnt lgkmcnt(14)
	v_fma_f32 v180, -v72, v179, v180
	v_fma_f32 v181, v72, v178, v181
	v_fma_f32 v180, v74, v178, v180
	v_fma_f32 v181, v74, v179, v181
	v_cvt_pk_bf16_f32 v197, v180, v181
	ds_write_b32 v97, v197 offset:10624
	s_waitcnt lgkmcnt(13)
	v_fma_f32 v182, -v72, v181, v182
	v_fma_f32 v183, v72, v180, v183
	v_fma_f32 v182, v74, v180, v182
	v_fma_f32 v183, v74, v181, v183
	v_cvt_pk_bf16_f32 v198, v182, v183
	ds_write_b32 v97, v198 offset:10896
	s_waitcnt lgkmcnt(12)
	v_fma_f32 v184, -v72, v183, v184
	v_fma_f32 v185, v72, v182, v185
	v_fma_f32 v184, v74, v182, v184
	v_fma_f32 v185, v74, v183, v185
	v_cvt_pk_bf16_f32 v197, v184, v185
	ds_write_b32 v97, v197 offset:11168
	s_waitcnt lgkmcnt(11)
	v_fma_f32 v186, -v72, v185, v186
	v_fma_f32 v187, v72, v184, v187
	v_fma_f32 v186, v74, v184, v186
	v_fma_f32 v187, v74, v185, v187
	v_cvt_pk_bf16_f32 v198, v186, v187
	ds_write_b32 v97, v198 offset:11440
	s_waitcnt lgkmcnt(10)
	v_fma_f32 v188, -v72, v187, v188
	v_fma_f32 v189, v72, v186, v189
	v_fma_f32 v188, v74, v186, v188
	v_fma_f32 v189, v74, v187, v189
	v_cvt_pk_bf16_f32 v197, v188, v189
	ds_write_b32 v97, v197 offset:11712
	s_waitcnt lgkmcnt(9)
	v_fma_f32 v190, -v72, v189, v190
	v_fma_f32 v191, v72, v188, v191
	v_fma_f32 v190, v74, v188, v190
	v_fma_f32 v191, v74, v189, v191
	v_cvt_pk_bf16_f32 v198, v190, v191
	ds_write_b32 v97, v198 offset:11984
	s_waitcnt lgkmcnt(8)
	v_fma_f32 v192, -v72, v191, v192
	v_fma_f32 v193, v72, v190, v193
	v_fma_f32 v192, v74, v190, v192
	v_fma_f32 v193, v74, v191, v193
	v_cvt_pk_bf16_f32 v197, v192, v193
	ds_write_b32 v97, v197 offset:12256
	s_waitcnt lgkmcnt(7)
	v_fma_f32 v194, -v72, v193, v194
	v_fma_f32 v195, v72, v192, v195
	v_fma_f32 v194, v74, v192, v194
	v_fma_f32 v195, v74, v193, v195
	v_cvt_pk_bf16_f32 v198, v194, v195
	ds_write_b32 v97, v198 offset:12528
	s_branch .Ls5l_join

.Ls5l_join:
	v_mov_b32_e32 v120, v194
	v_mov_b32_e32 v121, v195
	v_add_u32_e32 v196, v99, v93
	ds_read_b128 v[132:135], v196 offset:8448
	ds_read_b128 v[136:139], v196 offset:8512
	ds_read_b128 v[140:143], v196 offset:8576
	ds_read_b128 v[144:147], v196 offset:8640
	s_not_b32 s12, s4
	s_add_i32 s15, s3, s12
	s_and_b64 s[12:13], s[54:55], exec
	s_cselect_b32 s12, s4, s15
	s_add_i32 s4, s4, 1
	s_waitcnt lgkmcnt(3)
	v_mfma_f32_16x16x32_bf16 v[68:71], v[48:51], v[132:135], 0
	s_waitcnt lgkmcnt(2)
	v_mfma_f32_16x16x32_bf16 v[68:71], v[52:55], v[136:139], v[68:71]
	s_waitcnt lgkmcnt(1)
	v_mfma_f32_16x16x32_bf16 v[68:71], v[56:59], v[140:143], v[68:71]
	s_waitcnt lgkmcnt(0)
	v_mfma_f32_16x16x32_bf16 v[68:71], v[60:63], v[144:147], v[68:71]
	v_lshl_add_u32 v200, s12, 4, v2
	v_ashrrev_i32_e32 v201, 31, v200
	v_lshlrev_b64 v[200:201], 12, v[200:201]
	v_lshl_add_u64 v[200:201], v[78:79], 0, v[200:201]
	s_nop 3
	v_cvt_pk_bf16_f32 v68, v68, v69
	v_cvt_pk_bf16_f32 v69, v70, v71
	global_store_dwordx2 v[200:201], v[68:69], off
	s_cmp_eq_u32 s4, s3
	s_cbranch_scc1 .LBB0_916
	v_mov_b32_e32 v68, v36
	v_mov_b32_e32 v69, v37
	v_mov_b32_e32 v70, v38
	v_mov_b32_e32 v71, v39
	v_mov_b32_e32 v36, v40
	v_mov_b32_e32 v37, v41
	v_mov_b32_e32 v38, v42
	v_mov_b32_e32 v39, v43
	v_mov_b32_e32 v40, v44
	v_mov_b32_e32 v41, v45
	v_mov_b32_e32 v42, v46
	v_mov_b32_e32 v43, v47
	s_waitcnt vmcnt(1)
	v_mov_b32_e32 v44, v64
	v_mov_b32_e32 v45, v65
	v_mov_b32_e32 v46, v66
	v_mov_b32_e32 v47, v67
	s_branch .LBB0_909
